# RWKV scan loops: serial lane-xor (1,2,4) ds_bpermute reduction steps replaced by v_mov_b32_dpp quad_perm / row_half_mirror (9 sites)
# speedup vs baseline: 1.0133x; 1.0090x over previous
; template <bool PA> ...
;     ...
;             float rv[8], kk[8], av[8], kd[8], lw[8]; u32x4_t tld = (u32x4_t){0u, 0u, 0u, 0u}, vraw = (u32x4_t){0u, 0u, 0u, 0u};
;             {
;                 const size_t row = cbase + (d ? 63 - j : j);
;                 asm volatile("" ::: "memory");
;                 if (haveT && tlow) tld = *(const u32x4_t*)(tbuf + ((size_t)strm * NCHA + p) * 2304 + tunit * 8);
;                 *(u32x4_t*)(MAT(4) + j * 72 + c8) = *(const u32x4_t*)(HWb + row * 128 + d * 64 + c8);
;                 *(u32x4_t*)(MAT(5) + j * 72 + c8) = *(const u32x4_t*)(HAb + row * 128 + d * 64 + c8);
;                 const u32x4_t rw = *(const u32x4_t*)(Rb + row * 1024 + hc8), kw = *(const u32x4_t*)(Kb + row * 1024 + hc8), vw = *(const u32x4_t*)(Vb + row * 1024 + hc8);
;                 __syncthreads();
;                 { f32x4_t za[2], xa[2]; za[0] = (f32x4_t){0.f, 0.f, 0.f, 0.f}; za[1] = za[0]; xa[0] = za[0]; xa[1] = za[0];
;                   mm2(za, MAT(4), w2T, mt, ntb, r16, kq); mm2(xa, MAT(5), a2T, mt, ntb, r16, kq);
; #pragma unroll
;                   for (int i = 0; i < 2; ++i)
; #pragma unroll
;                       for (int e = 0; e < 4; ++e) { zbuf[(16 * mt + 4 * kq + e) * 64 + 16 * (ntb + i) + r16] = za[i][e]; abuf[(16 * mt + 4 * kq + e) * 64 + 16 * (ntb + i) + r16] = xa[i][e]; } }
;                 __syncthreads();
.LBB0_153:
	s_nop 0
	s_waitcnt vmcnt(2)
	ds_write_b128 v91, v[232:235] offset:36864
	ds_write_b128 v91, v[236:239] offset:46080
	v_mov_b32_e32 v10, v228
	v_mov_b32_e32 v11, v229
	v_mov_b32_e32 v12, v230
	v_mov_b32_e32 v13, v231
	v_mov_b32_e32 v18, v240
	v_mov_b32_e32 v19, v241
	v_mov_b32_e32 v20, v242
	v_mov_b32_e32 v21, v243
	v_mov_b32_e32 v22, v244
	v_mov_b32_e32 v23, v245
	v_mov_b32_e32 v24, v246
	v_mov_b32_e32 v25, v247
	v_mov_b32_e32 v14, v248
	v_mov_b32_e32 v15, v249
	v_mov_b32_e32 v16, v250
	v_mov_b32_e32 v17, v251
	s_and_b64 s[0:1], vcc, exec
	s_cselect_b32 s0, s12, s18
	s_cselect_b32 s1, 64, 0xffffffc0
	v_lshl_add_u32 v80, s0, 6, v130
	v_ashrrev_i32_e32 v81, 31, v80
	s_add_i32 s0, s12, 1
	s_cmp_lt_i32 s0, s13
	s_cselect_b32 s1, s1, 0
	v_add_u32_e32 v226, s1, v80
	s_and_saveexec_b64 s[0:1], s[36:37]
	global_load_dwordx4 v[228:231], v[78:79], off
	s_or_b64 exec, exec, s[0:1]
	v_ashrrev_i32_e32 v227, 31, v226
	v_lshlrev_b64 v[224:225], 8, v[226:227]
	v_lshl_add_u64 v[222:223], v[66:67], 0, v[224:225]
	global_load_dwordx4 v[232:235], v[222:223], off
	v_lshl_add_u64 v[222:223], v[68:69], 0, v[224:225]
	global_load_dwordx4 v[236:239], v[222:223], off
	v_lshlrev_b64 v[224:225], 11, v[226:227]
	v_lshl_add_u64 v[222:223], v[70:71], 0, v[224:225]
	global_load_dwordx4 v[240:243], v[222:223], off
	v_lshl_add_u64 v[222:223], v[72:73], 0, v[224:225]
	global_load_dwordx4 v[244:247], v[222:223], off
	v_lshl_add_u64 v[222:223], v[74:75], 0, v[224:225]
	global_load_dwordx4 v[248:251], v[222:223], off
	s_waitcnt lgkmcnt(0)
	s_barrier
	ds_read_b128 v[178:181], v92 offset:36864
	ds_read_b128 v[182:185], v93
	ds_read_b128 v[186:189], v93 offset:2304
	ds_read_b128 v[190:193], v92 offset:36928
	ds_read_b128 v[204:207], v93 offset:64
	ds_read_b128 v[208:211], v93 offset:2368
	ds_read_b128 v[212:215], v92 offset:46080
	ds_read_b128 v[216:219], v94
	ds_read_b128 v[220:223], v94 offset:2304
	ds_read_b128 v[224:227], v92 offset:46144
	s_nop 0
	s_nop 0
	s_nop 0
	s_waitcnt lgkmcnt(8)
	v_mfma_f32_16x16x32_bf16 v[30:33], v[178:181], v[182:185], 0
	ds_read_b128 v[182:185], v94 offset:64
	s_nop 0
	v_lshlrev_b32_e32 v0, 16, v18
	s_waitcnt lgkmcnt(8)
	v_mfma_f32_16x16x32_bf16 v[26:29], v[178:181], v[186:189], 0
	ds_read_b128 v[178:181], v94 offset:2368
	s_nop 0
	s_nop 0
	v_and_b32_e32 v131, 0xffff0000, v18
	s_nop 0
	v_and_b32_e32 v162, 0xffff0000, v24
	s_waitcnt lgkmcnt(7)
	v_mfma_f32_16x16x32_bf16 v[30:33], v[190:193], v[204:207], v[30:33]
	s_nop 0
	v_lshlrev_b32_e32 v141, 16, v21
	v_and_b32_e32 v143, 0xffff0000, v21
	s_waitcnt lgkmcnt(6)
	v_mfma_f32_16x16x32_bf16 v[26:29], v[190:193], v[208:211], v[26:29]
	s_nop 0
	s_nop 0
	s_nop 0
	v_lshlrev_b32_e32 v158, 16, v25
	s_waitcnt lgkmcnt(4)
	v_mfma_f32_16x16x32_bf16 v[38:41], v[212:215], v[216:219], 0
	v_and_b32_e32 v154, 0xffff0000, v25
	s_waitcnt lgkmcnt(3)
	v_mfma_f32_16x16x32_bf16 v[34:37], v[212:215], v[220:223], 0
	s_nop 0
	s_nop 0
	s_waitcnt lgkmcnt(1)
	v_mfma_f32_16x16x32_bf16 v[38:41], v[224:227], v[182:185], v[38:41]
	s_nop 0
	s_waitcnt lgkmcnt(0)
	v_mfma_f32_16x16x32_bf16 v[34:37], v[224:227], v[178:181], v[34:37]
	s_nop 4
	ds_write2st64_b32 v119, v30, v38 offset1:64
	ds_write2st64_b32 v120, v31, v39 offset1:64
	ds_write2st64_b32 v121, v32, v40 offset1:64
	ds_write2st64_b32 v122, v33, v41 offset1:64
	ds_write2st64_b32 v123, v26, v34 offset1:64
	ds_write2st64_b32 v124, v27, v35 offset1:64
	ds_write2st64_b32 v125, v28, v36 offset1:64
	ds_write2st64_b32 v126, v29, v37 offset1:64
	s_waitcnt lgkmcnt(0)
	s_barrier
; __device__ __forceinline__ float sigmoidf_(float x) { return __builtin_amdgcn_rcpf(1.0f + __expf(-x)); }
; template <bool PA> ...
;     ...
;                 float ss = 0.f, bsum = 0.f;
; #pragma unroll
;                 for (int e = 0; e < 8; ++e) { kk[e] = kv[e] * cst[128 + c8 + e]; ss += kk[e] * kk[e]; }
;                 ss += __shfl_xor(ss, 1); ss += __shfl_xor(ss, 2); ss += __shfl_xor(ss, 4);
;                 const float inv = rsqrtf(fmaxf(ss, 1e-24f));
; #pragma unroll
;                 for (int e = 0; e < 8; ++e) { av[e] = sigmoidf_(aa[e]); lw[e] = -0.6065306597f * sigmoidf_(z[e]); kd[e] = kv[e] * (1.0f + (av[e] - 1.0f) * cst[192 + c8 + e]); kk[e] *= inv; bsum += rv[e] * kd[e] * cst[256 + c8 + e]; }
;                 bsum += __shfl_xor(bsum, 1); bsum += __shfl_xor(bsum, 2); bsum += __shfl_xor(bsum, 4);
;                 if (!PA && part == 0) beta[((size_t)d * SLAB + row) * 16 + head] = bsum;
	v_lshlrev_b32_e32 v39, 16, v22
	v_and_b32_e32 v36, 0xffff0000, v22
	v_lshlrev_b32_e32 v133, 16, v19
	v_and_b32_e32 v135, 0xffff0000, v19
	v_lshlrev_b32_e32 v35, 16, v23
	v_and_b32_e32 v34, 0xffff0000, v23
	v_lshlrev_b32_e32 v137, 16, v20
	v_and_b32_e32 v139, 0xffff0000, v20
	v_lshlrev_b32_e32 v38, 16, v24
	ds_read_b128 v[18:21], v95
	ds_read_b128 v[22:25], v95 offset:16
	ds_read_b128 v[144:147], v95 offset:16384
	ds_read_b128 v[148:151], v95 offset:16400
	ds_read_b128 v[26:29], v96
	ds_read_b128 v[30:33], v96 offset:16
	ds_read_b128 v[164:167], v96 offset:256
	ds_read_b128 v[168:171], v96 offset:272
	s_waitcnt lgkmcnt(1)
	v_add_f32_e32 v153, v144, v164
	s_waitcnt lgkmcnt(0)
	v_add_f32_e32 v37, v148, v168
	v_add_f32_e32 v152, v145, v165
	v_add_f32_e32 v164, v149, v169
	v_add_f32_e32 v41, v146, v166
	v_add_f32_e32 v161, v150, v170
	v_add_f32_e32 v40, v147, v167
	v_add_f32_e32 v157, v151, v171
	ds_read_b128 v[144:147], v96 offset:512
	ds_read_b128 v[148:151], v96 offset:528
	ds_read_b128 v[168:171], v96 offset:768
	ds_read_b128 v[172:175], v96 offset:1024
	s_waitcnt lgkmcnt(3)
	v_mul_f32_e32 v134, v145, v36
	v_mul_f32_e32 v132, v144, v39
	v_mul_f32_e32 v155, v134, v134
	v_fmac_f32_e32 v155, v132, v132
	v_mul_f32_e32 v136, v146, v35
	v_fmac_f32_e32 v155, v136, v136
	v_mul_f32_e32 v138, v147, v34
	v_fmac_f32_e32 v155, v138, v138
	s_waitcnt lgkmcnt(2)
	v_mul_f32_e32 v140, v148, v38
	v_and_b32_e32 v147, 64, v198
	v_fmac_f32_e32 v155, v140, v140
	v_mul_f32_e32 v142, v149, v162
	v_xor_b32_e32 v146, 1, v198
	v_add_u32_e32 v147, 64, v147
	v_fmac_f32_e32 v155, v142, v142
	v_mul_f32_e32 v144, v150, v158
	v_cmp_lt_i32_e64 s[92:93], v146, v147
	v_fmac_f32_e32 v155, v144, v144
	v_mul_f32_e32 v145, v151, v154
	v_cndmask_b32_e64 v146, v198, v146, s[92:93]
	v_fmac_f32_e32 v155, v145, v145
	v_lshlrev_b32_e32 v146, 2, v146
	s_nop 1
	v_mov_b32_dpp v148, v155 quad_perm:[1,0,3,2] row_mask:0xf bank_mask:0xf
	v_xor_b32_e32 v149, 2, v198
	v_cmp_lt_i32_e64 s[92:93], v149, v147
	s_waitcnt lgkmcnt(0)
	v_add_f32_e32 v148, v155, v148
	v_cndmask_b32_e64 v149, v198, v149, s[92:93]
	v_lshlrev_b32_e32 v166, 2, v149
	s_nop 1
	v_mov_b32_dpp v149, v148 quad_perm:[2,3,0,1] row_mask:0xf bank_mask:0xf
	s_waitcnt lgkmcnt(0)
	v_add_f32_e32 v149, v148, v149
	v_xor_b32_e32 v148, 4, v198
	v_cmp_lt_i32_e64 s[92:93], v148, v147
	s_nop 1
	v_cndmask_b32_e64 v147, v198, v148, s[92:93]
	v_mul_f32_e32 v148, 0xbfb8aa3b, v153
	v_exp_f32_e32 v148, v148
	v_lshlrev_b32_e32 v147, 2, v147
	s_nop 1
	v_mov_b32_dpp v150, v149 row_half_mirror row_mask:0xf bank_mask:0xf
	v_add_f32_e32 v148, 1.0, v148
	v_rcp_f32_e32 v148, v148
	s_nop 0
	v_add_f32_e32 v151, -1.0, v148
	v_fma_f32 v151, v151, v168, 1.0
	v_mul_f32_e32 v151, v151, v39
	v_mul_f32_e32 v39, v151, v0
	v_fma_f32 v167, v172, v39, 0
	v_mul_f32_e32 v39, 0xbfb8aa3b, v152
	v_exp_f32_e32 v39, v39
	s_nop 0
	v_add_f32_e32 v39, 1.0, v39
	v_rcp_f32_e32 v152, v39
	s_nop 0
	v_add_f32_e32 v39, -1.0, v152
	v_fma_f32 v39, v39, v169, 1.0
	v_mul_f32_e32 v153, v39, v36
	v_mul_f32_e32 v36, v153, v131
	v_fmac_f32_e32 v167, v173, v36
	v_mul_f32_e32 v36, 0xbfb8aa3b, v41
	v_exp_f32_e32 v36, v36
	s_nop 0
	v_add_f32_e32 v36, 1.0, v36
	v_rcp_f32_e32 v155, v36
	s_nop 0
	v_add_f32_e32 v36, -1.0, v155
	v_fma_f32 v36, v36, v170, 1.0
	v_mul_f32_e32 v156, v36, v35
	v_mul_f32_e32 v35, v156, v133
	v_fmac_f32_e32 v167, v174, v35
	v_mul_f32_e32 v35, 0xbfb8aa3b, v40
	v_exp_f32_e32 v35, v35
	s_nop 0
	v_add_f32_e32 v35, 1.0, v35
	v_rcp_f32_e32 v159, v35
	s_nop 0
	v_add_f32_e32 v35, -1.0, v159
	v_fma_f32 v35, v35, v171, 1.0
	v_mul_f32_e32 v160, v35, v34
	v_mul_f32_e32 v34, v160, v135
	v_fmac_f32_e32 v167, v175, v34
	v_mul_f32_e32 v34, 0xbfb8aa3b, v37
	v_exp_f32_e32 v34, v34
	s_nop 0
	v_add_f32_e32 v34, 1.0, v34
	v_rcp_f32_e32 v163, v34
	ds_read_b128 v[34:37], v96 offset:784
	v_add_f32_e32 v39, -1.0, v163
	s_waitcnt lgkmcnt(0)
	v_fma_f32 v34, v39, v34, 1.0
	v_mul_f32_e32 v165, v34, v38
	ds_read_b128 v[38:41], v96 offset:1040
	v_mul_f32_e32 v34, v165, v137
	s_waitcnt lgkmcnt(0)
	v_fmac_f32_e32 v167, v38, v34
	v_mul_f32_e32 v34, 0xbfb8aa3b, v164
	v_exp_f32_e32 v34, v34
	s_nop 0
	v_add_f32_e32 v34, 1.0, v34
	v_rcp_f32_e32 v38, v34
	s_nop 0
	v_add_f32_e32 v34, -1.0, v38
	v_fma_f32 v34, v34, v35, 1.0
	v_mul_f32_e32 v162, v34, v162
	v_mul_f32_e32 v34, v162, v139
	v_fmac_f32_e32 v167, v39, v34
	v_mul_f32_e32 v34, 0xbfb8aa3b, v161
	v_exp_f32_e32 v34, v34
	s_nop 0
	v_add_f32_e32 v34, 1.0, v34
	v_rcp_f32_e32 v39, v34
	s_nop 0
	v_add_f32_e32 v34, -1.0, v39
	v_fma_f32 v34, v34, v36, 1.0
	v_mul_f32_e32 v36, v34, v158
	v_mul_f32_e32 v34, v36, v141
	v_fmac_f32_e32 v167, v40, v34
	v_mul_f32_e32 v34, 0xbfb8aa3b, v157
	v_exp_f32_e32 v34, v34
	s_nop 0
	v_add_f32_e32 v34, 1.0, v34
	v_rcp_f32_e32 v40, v34
	s_nop 0
	v_add_f32_e32 v34, -1.0, v40
	v_fma_f32 v34, v34, v37, 1.0
	v_mul_f32_e32 v37, v34, v154
	v_mul_f32_e32 v34, v37, v143
	v_fmac_f32_e32 v167, v41, v34
	s_nop 1
	v_mov_b32_dpp v34, v167 quad_perm:[1,0,3,2] row_mask:0xf bank_mask:0xf
	s_waitcnt lgkmcnt(0)
	v_add_f32_e32 v34, v167, v34
	s_nop 1
	v_mov_b32_dpp v35, v34 quad_perm:[2,3,0,1] row_mask:0xf bank_mask:0xf
	s_waitcnt lgkmcnt(0)
	v_add_f32_e32 v34, v34, v35
	s_nop 1
	v_mov_b32_dpp v35, v34 row_half_mirror row_mask:0xf bank_mask:0xf
	s_and_saveexec_b64 s[0:1], s[44:45]
	s_cbranch_execz .LBB0_157
	v_lshl_add_u64 v[146:147], s[24:25], 0, v[80:81]
	v_lshlrev_b64 v[146:147], 6, v[146:147]
	v_lshl_add_u64 v[146:147], s[20:21], 0, v[146:147]
	s_waitcnt lgkmcnt(0)
	v_add_f32_e32 v34, v34, v35
	global_store_dword v[146:147], v34, off

; template <bool PA> ...
;     ...
;             float rv[8], kk[8], av[8], kd[8], lw[8]; u32x4_t tld = (u32x4_t){0u, 0u, 0u, 0u}, vraw = (u32x4_t){0u, 0u, 0u, 0u};
;             {
;                 const size_t row = cbase + (d ? 63 - j : j);
;                 asm volatile("" ::: "memory");
;                 if (haveT && tlow) tld = *(const u32x4_t*)(tbuf + ((size_t)strm * NCHA + p) * 2304 + tunit * 8);
;                 *(u32x4_t*)(MAT(4) + j * 72 + c8) = *(const u32x4_t*)(HWb + row * 128 + d * 64 + c8);
;                 *(u32x4_t*)(MAT(5) + j * 72 + c8) = *(const u32x4_t*)(HAb + row * 128 + d * 64 + c8);
;                 const u32x4_t rw = *(const u32x4_t*)(Rb + row * 1024 + hc8), kw = *(const u32x4_t*)(Kb + row * 1024 + hc8), vw = *(const u32x4_t*)(Vb + row * 1024 + hc8);
;                 __syncthreads();
;                 { f32x4_t za[2], xa[2]; za[0] = (f32x4_t){0.f, 0.f, 0.f, 0.f}; za[1] = za[0]; xa[0] = za[0]; xa[1] = za[0];
;                   mm2(za, MAT(4), w2T, mt, ntb, r16, kq); mm2(xa, MAT(5), a2T, mt, ntb, r16, kq);
; #pragma unroll
;                   for (int i = 0; i < 2; ++i)
; #pragma unroll
;                       for (int e = 0; e < 4; ++e) { zbuf[(16 * mt + 4 * kq + e) * 64 + 16 * (ntb + i) + r16] = za[i][e]; abuf[(16 * mt + 4 * kq + e) * 64 + 16 * (ntb + i) + r16] = xa[i][e]; } }
;                 __syncthreads();
.LBB0_213:
	s_waitcnt vmcnt(1)
	ds_write_b128 v68, v[232:235] offset:36864
	ds_write_b128 v68, v[236:239] offset:46080
	v_mov_b32_e32 v22, v240
	v_mov_b32_e32 v23, v241
	v_mov_b32_e32 v24, v242
	v_mov_b32_e32 v25, v243
	v_mov_b32_e32 v26, v244
	v_mov_b32_e32 v27, v245
	v_mov_b32_e32 v28, v246
	v_mov_b32_e32 v29, v247
	v_mov_b32_e32 v18, v248
	v_mov_b32_e32 v19, v249
	v_mov_b32_e32 v20, v250
	v_mov_b32_e32 v21, v251
	s_and_b64 s[12:13], s[74:75], exec
	s_cselect_b32 s12, s20, s24
	s_cselect_b32 s13, 64, 0xffffffc0
	v_lshl_add_u32 v226, s12, 6, v160
	s_add_i32 s12, s20, 1
	s_cmp_lt_i32 s12, s21
	s_cselect_b32 s13, s13, 0
	v_add_u32_e32 v226, s13, v226
	v_ashrrev_i32_e32 v227, 31, v226
	v_lshlrev_b64 v[224:225], 8, v[226:227]
	v_lshl_add_u64 v[222:223], v[90:91], 0, v[224:225]
	global_load_dwordx4 v[232:235], v[222:223], off
	v_lshl_add_u64 v[222:223], v[92:93], 0, v[224:225]
	global_load_dwordx4 v[236:239], v[222:223], off
	v_lshlrev_b64 v[224:225], 11, v[226:227]
	v_lshl_add_u64 v[222:223], v[94:95], 0, v[224:225]
	global_load_dwordx4 v[240:243], v[222:223], off
	v_lshl_add_u64 v[222:223], v[96:97], 0, v[224:225]
	global_load_dwordx4 v[244:247], v[222:223], off
	v_lshl_add_u64 v[222:223], v[98:99], 0, v[224:225]
	global_load_dwordx4 v[248:251], v[222:223], off
	s_waitcnt lgkmcnt(0)
	s_barrier
	ds_read_b128 v[186:189], v69 offset:36864
	ds_read_b128 v[190:193], v108
	ds_read_b128 v[204:207], v108 offset:2304
	ds_read_b128 v[208:211], v69 offset:36928
	ds_read_b128 v[212:215], v108 offset:64
	ds_read_b128 v[216:219], v108 offset:2368
	ds_read_b128 v[220:223], v69 offset:46080
	ds_read_b128 v[224:227], v109
	s_nop 0
	s_nop 0
	s_nop 0
	s_waitcnt lgkmcnt(6)
	v_mfma_f32_16x16x32_bf16 v[34:37], v[186:189], v[190:193], 0
	ds_read_b128 v[190:193], v109 offset:2304
	s_nop 0
	v_lshlrev_b32_e32 v161, 16, v26
	s_waitcnt lgkmcnt(6)
	v_mfma_f32_16x16x32_bf16 v[30:33], v[186:189], v[204:207], 0
	ds_read_b128 v[186:189], v69 offset:46144
	ds_read_b128 v[204:207], v109 offset:64
	s_nop 0
	s_nop 0
	v_and_b32_e32 v163, 0xffff0000, v26
	v_lshlrev_b32_e32 v165, 16, v27
	s_waitcnt lgkmcnt(6)
	v_mfma_f32_16x16x32_bf16 v[34:37], v[208:211], v[212:215], v[34:37]
	ds_read_b128 v[212:215], v109 offset:2368
	s_nop 0
	v_and_b32_e32 v167, 0xffff0000, v27
	v_lshlrev_b32_e32 v169, 16, v28
	s_waitcnt lgkmcnt(6)
	v_mfma_f32_16x16x32_bf16 v[30:33], v[208:211], v[216:219], v[30:33]
	s_nop 0
	s_nop 0
	s_nop 0
	v_and_b32_e32 v171, 0xffff0000, v28
	s_waitcnt lgkmcnt(4)
	v_mfma_f32_16x16x32_bf16 v[42:45], v[220:223], v[224:227], 0
	v_lshlrev_b32_e32 v173, 16, v29
	v_and_b32_e32 v175, 0xffff0000, v29
	s_waitcnt lgkmcnt(3)
	v_mfma_f32_16x16x32_bf16 v[38:41], v[220:223], v[190:193], 0
	s_nop 0
	s_nop 0
	s_waitcnt lgkmcnt(1)
	v_mfma_f32_16x16x32_bf16 v[42:45], v[186:189], v[204:207], v[42:45]
	s_nop 0
	s_waitcnt lgkmcnt(0)
	v_mfma_f32_16x16x32_bf16 v[38:41], v[186:189], v[212:215], v[38:41]
	s_nop 4
	ds_write2st64_b32 v144, v34, v42 offset1:64
	ds_write2st64_b32 v145, v35, v43 offset1:64
	ds_write2st64_b32 v148, v36, v44 offset1:64
	ds_write2st64_b32 v149, v37, v45 offset1:64
	ds_write2st64_b32 v150, v30, v38 offset1:64
	ds_write2st64_b32 v151, v31, v39 offset1:64
	ds_write2st64_b32 v152, v32, v40 offset1:64
	ds_write2st64_b32 v153, v33, v41 offset1:64
	s_waitcnt lgkmcnt(0)
	s_barrier
; __device__ __forceinline__ float sigmoidf_(float x) { return __builtin_amdgcn_rcpf(1.0f + __expf(-x)); }
; template <bool PA> ...
;     ...
;                 float ss = 0.f, bsum = 0.f;
; #pragma unroll
;                 for (int e = 0; e < 8; ++e) { kk[e] = kv[e] * cst[128 + c8 + e]; ss += kk[e] * kk[e]; }
;                 ss += __shfl_xor(ss, 1); ss += __shfl_xor(ss, 2); ss += __shfl_xor(ss, 4);
;                 const float inv = rsqrtf(fmaxf(ss, 1e-24f));
; #pragma unroll
;                 for (int e = 0; e < 8; ++e) { av[e] = sigmoidf_(aa[e]); lw[e] = -0.6065306597f * sigmoidf_(z[e]); kd[e] = kv[e] * (1.0f + (av[e] - 1.0f) * cst[192 + c8 + e]); kk[e] *= inv; bsum += rv[e] * kd[e] * cst[256 + c8 + e]; }
;                 bsum += __shfl_xor(bsum, 1); bsum += __shfl_xor(bsum, 2); bsum += __shfl_xor(bsum, 4);
;                 if (!PA && part == 0) beta[((size_t)d * SLAB + row) * 16 + head] = bsum;
;                 *(f32x4_t*)(cumb + j * 64 + c8) = (f32x4_t){lw[0], lw[1], lw[2], lw[3]}; *(f32x4_t*)(cumb + j * 64 + c8 + 4) = (f32x4_t){lw[4], lw[5], lw[6], lw[7]};
;             }
;             __syncthreads();
;             { const int c = tid & 63, sg = tid >> 6; float run = 0.f;
; #pragma unroll
;               for (int i = 0; i < 8; ++i) { run += cumb[(8 * sg + i) * 64 + c]; cumb[(8 * sg + i) * 64 + c] = run; }
;               segtot[sg * 64 + c] = run; }
;             __syncthreads();
;             { const int c = tid & 63, sg = tid >> 6; float off = 0.f;
; #pragma unroll
;               for (int s = 0; s < 7; ++s) off += (s < sg) ? segtot[s * 64 + c] : 0.f;
; #pragma unroll
;               for (int i = 0; i < 8; ++i) cumb[(8 * sg + i) * 64 + c] += off; }
	ds_read_b128 v[186:189], v110
	ds_read_b128 v[190:193], v110 offset:16
	ds_read_b128 v[204:207], v111
	ds_read_b128 v[208:211], v111 offset:16
	ds_read_b128 v[212:215], v111 offset:512
	ds_read_b128 v[216:219], v111 offset:528
	s_nop 0
	s_nop 0
	ds_read_b128 v[26:29], v110 offset:16384
	ds_read_b128 v[30:33], v110 offset:16400
	s_nop 0
	s_nop 0
	ds_read_b128 v[34:37], v111 offset:256
	ds_read_b128 v[38:41], v111 offset:272
	s_waitcnt lgkmcnt(2)
	v_add_f32_e32 v42, v186, v204
	s_waitcnt lgkmcnt(2)
	v_add_f32_e32 v50, v190, v208
	v_add_f32_e32 v46, v187, v205
	v_add_f32_e32 v54, v191, v209
	v_add_f32_e32 v49, v188, v206
	v_add_f32_e32 v57, v192, v210
	v_add_f32_e32 v48, v189, v207
	v_add_f32_e32 v56, v193, v211
	s_nop 0
	s_nop 0
	v_and_b32_e32 v45, 64, v198
	v_xor_b32_e32 v44, 1, v198
	v_add_u32_e32 v45, 64, v45
	s_waitcnt lgkmcnt(0)
	v_mul_f32_e32 v164, v213, v163
	v_mul_f32_e32 v162, v212, v161
	v_mul_f32_e32 v43, v164, v164
	v_fmac_f32_e32 v43, v162, v162
	v_mul_f32_e32 v166, v214, v165
	v_fmac_f32_e32 v43, v166, v166
	v_mul_f32_e32 v168, v215, v167
	v_mov_b32_e32 v61, v215
	v_fmac_f32_e32 v43, v168, v168
	s_waitcnt lgkmcnt(0)
	v_mul_f32_e32 v170, v216, v169
	v_fmac_f32_e32 v43, v170, v170
	v_mul_f32_e32 v172, v217, v171
	v_fmac_f32_e32 v43, v172, v172
	v_mul_f32_e32 v174, v218, v173
	v_cmp_lt_i32_e64 s[76:77], v44, v45
	v_fmac_f32_e32 v43, v174, v174
	v_mul_f32_e32 v176, v219, v175
	v_mov_b32_e32 v62, v216
	v_mov_b32_e32 v63, v217
	v_mov_b32_e32 v64, v218
	v_mov_b32_e32 v65, v219
	v_cndmask_b32_e64 v44, v198, v44, s[76:77]
	v_fmac_f32_e32 v43, v176, v176
	v_lshlrev_b32_e32 v44, 2, v44
	s_nop 1
	v_mov_b32_dpp v44, v43 quad_perm:[1,0,3,2] row_mask:0xf bank_mask:0xf
	v_mul_f32_e32 v42, 0xbfb8aa3b, v42
	v_mul_f32_e32 v46, 0xbfb8aa3b, v46
	v_exp_f32_e32 v42, v42
	v_exp_f32_e32 v46, v46
	v_mul_f32_e32 v50, 0xbfb8aa3b, v50
	v_mul_f32_e32 v54, 0xbfb8aa3b, v54
	s_waitcnt lgkmcnt(0)
	v_add_f32_e32 v43, v43, v44
	v_xor_b32_e32 v44, 2, v198
	v_exp_f32_e32 v50, v50
	v_exp_f32_e32 v54, v54
	v_cmp_lt_i32_e64 s[76:77], v44, v45
	v_mul_f32_e32 v49, 0xbfb8aa3b, v49
	v_mul_f32_e32 v48, 0xbfb8aa3b, v48
	v_cndmask_b32_e64 v44, v198, v44, s[76:77]
	v_lshlrev_b32_e32 v44, 2, v44
	v_add_f32_e32 v42, 1.0, v42
	v_add_f32_e32 v46, 1.0, v46
	v_exp_f32_e32 v49, v49
	v_exp_f32_e32 v48, v48
	v_mul_f32_e32 v57, 0xbfb8aa3b, v57
	v_mul_f32_e32 v56, 0xbfb8aa3b, v56
	s_nop 1
	v_mov_b32_dpp v44, v43 quad_perm:[2,3,0,1] row_mask:0xf bank_mask:0xf
	v_rcp_f32_e32 v52, v42
	v_rcp_f32_e32 v53, v46
	v_add_f32_e32 v50, 1.0, v50
	v_add_f32_e32 v54, 1.0, v54
	v_exp_f32_e32 v57, v57
	v_exp_f32_e32 v56, v56
	v_rcp_f32_e32 v58, v50
	v_rcp_f32_e32 v59, v54
	v_add_f32_e32 v49, 1.0, v49
	v_add_f32_e32 v48, 1.0, v48
	v_pk_mul_f32 v[46:47], v[52:53], s[30:31] op_sel_hi:[1,0]
	v_rcp_f32_e32 v52, v49
	v_rcp_f32_e32 v53, v48
	v_add_f32_e32 v57, 1.0, v57
	v_add_f32_e32 v56, 1.0, v56
	s_waitcnt lgkmcnt(0)
	v_add_f32_e32 v146, v43, v44
	v_xor_b32_e32 v43, 4, v198
	v_pk_mul_f32 v[54:55], v[58:59], s[30:31] op_sel_hi:[1,0]
	v_rcp_f32_e32 v58, v57
	v_rcp_f32_e32 v59, v56
	v_cmp_lt_i32_e64 s[76:77], v43, v45
	v_pk_mul_f32 v[48:49], v[52:53], s[30:31] op_sel_hi:[1,0]
	ds_read_b128 v[50:53], v111 offset:784
	v_cndmask_b32_e64 v43, v198, v43, s[76:77]
	v_lshlrev_b32_e32 v43, 2, v43
	s_nop 1
	v_mov_b32_dpp v147, v146 row_half_mirror row_mask:0xf bank_mask:0xf
	ds_read_b128 v[42:45], v111 offset:768
	v_pk_mul_f32 v[56:57], v[58:59], s[30:31] op_sel_hi:[1,0]
	ds_write_b128 v112, v[46:49]
	ds_write_b128 v112, v[54:57] offset:16
	s_waitcnt lgkmcnt(0)
	s_barrier
	ds_read2st64_b32 v[186:187], v159 offset1:1
	ds_read2st64_b32 v[188:189], v159 offset0:2 offset1:3
	ds_read2st64_b32 v[190:191], v159 offset0:4 offset1:5
	ds_read2st64_b32 v[192:193], v159 offset0:6 offset1:7
	s_nop 0
	s_waitcnt lgkmcnt(3)
	v_add_f32_e32 v58, 0, v186
	v_add_f32_e32 v60, v58, v187
	ds_write2st64_b32 v159, v58, v60 offset1:1
	s_nop 0
	s_waitcnt lgkmcnt(0)
	v_add_f32_e32 v58, v60, v188
	v_add_f32_e32 v60, v58, v189
	ds_write2st64_b32 v159, v58, v60 offset0:2 offset1:3
	s_nop 0
	s_waitcnt lgkmcnt(0)
	v_add_f32_e32 v58, v60, v190
	v_add_f32_e32 v60, v58, v191
	ds_write2st64_b32 v159, v58, v60 offset0:4 offset1:5
	s_nop 0
	s_waitcnt lgkmcnt(0)
	v_add_f32_e32 v58, v60, v192
	v_add_f32_e32 v59, v58, v193
	ds_write2st64_b32 v159, v58, v59 offset0:6 offset1:7
	ds_write_b32 v113, v59
	v_mov_b32_e32 v58, 0
	s_waitcnt lgkmcnt(0)
	s_barrier
	s_and_saveexec_b64 s[12:13], s[44:45]
	s_cbranch_execz .LBB0_215
	ds_read_b32 v58, v114
	s_waitcnt lgkmcnt(0)
	v_add_f32_e32 v58, 0, v58
